# sel: queue atomic issued after first tile loads, consumed at unit end
# baseline (speedup 1.0000x reference)
.LBB0_809:
	v_mov_b32_e32 v105, 0
	s_sub_i32 s6, s12, 64
	s_xor_b32 s6, s6, 0x3ff
	s_add_i32 s6, s6, 64
	s_cmp_lt_i32 s12, 64
	s_cselect_b32 s57, s12, s6
	v_mov_b32_e32 v106, v194
	s_cmp_gt_i32 s57, 63
	v_readfirstlane_b32 s40, v106
	s_mov_b64 s[8:9], -1
	s_cbranch_scc0 .LBB0_815
	s_sub_i32 s6, s57, 64
	s_lshr_b32 s12, s6, 10
	s_lshl_b32 s6, s6, 3
	s_and_b32 s41, s6, 0x1ff8
	s_lshl_b32 s7, s12, 13
	s_and_b32 s6, s6, 0x1fc0
	s_or_b32 s18, s7, s41
	s_add_i32 s19, s6, 64
	s_lshl_b64 s[6:7], s[12:13], 20
	s_add_u32 s6, s20, s6
	s_addc_u32 s7, s21, s7
	s_mov_b64 s[8:9], 0

.LBB0_817:
	v_bfe_u32 v0, v106, 2, 2
	v_add_u32_e32 v16, s18, v0
	v_and_b32_e32 v96, 48, v106
	v_ashrrev_i32_e32 v17, 31, v16
	v_and_b32_e32 v4, 3, v106
	v_lshl_add_u64 v[18:19], s[14:15], 0, v[96:97]
	v_lshlrev_b64 v[0:1], 5, v[16:17]
	v_lshlrev_b64 v[2:3], 10, v[16:17]
	v_lshl_add_u64 v[0:1], s[16:17], 0, v[0:1]
	v_lshl_add_u64 v[8:9], v[18:19], 0, v[2:3]
	v_lshlrev_b32_e32 v20, 2, v4
	v_mov_b32_e32 v21, v97
	v_lshlrev_b32_e32 v22, 7, v4
	v_mov_b32_e32 v23, v97
	v_lshl_add_u64 v[10:11], v[0:1], 0, v[20:21]
	v_lshl_add_u64 v[4:5], v[8:9], 0, v[22:23]
	global_load_dword v30, v[10:11], off
	global_load_dwordx4 v[0:3], v[4:5], off
	s_nop 0
	global_load_dwordx4 v[4:7], v[4:5], off offset:64
	v_mov_b32_e32 v25, v97
	v_or_b32_e32 v24, 0x200, v22
	v_lshl_add_u64 v[12:13], v[8:9], 0, v[24:25]
	global_load_dword v31, v[10:11], off offset:16
	s_nop 0
	global_load_dwordx4 v[8:11], v[12:13], off
	s_nop 0
	global_load_dwordx4 v[12:15], v[12:13], off offset:64
	v_add_u32_e32 v16, 4, v16
	v_ashrrev_i32_e32 v17, 31, v16
	v_lshlrev_b64 v[26:27], 5, v[16:17]
	v_lshlrev_b64 v[16:17], 10, v[16:17]
	v_lshl_add_u64 v[26:27], s[16:17], 0, v[26:27]
	v_lshl_add_u64 v[28:29], v[18:19], 0, v[16:17]
	v_lshl_add_u64 v[26:27], v[26:27], 0, v[20:21]
	v_lshl_add_u64 v[20:21], v[28:29], 0, v[22:23]
	global_load_dword v57, v[26:27], off
	global_load_dwordx4 v[16:19], v[20:21], off
	v_lshl_add_u64 v[28:29], v[28:29], 0, v[24:25]
	global_load_dwordx4 v[20:23], v[20:21], off offset:64
	s_nop 0
	global_load_dword v59, v[26:27], off offset:16
	s_nop 0
	global_load_dwordx4 v[24:27], v[28:29], off
	v_bfe_u32 v58, v106, 4, 2
	s_ashr_i32 s12, s40, 6
	s_mul_i32 s8, s12, 0x900
	v_mov_b32_e32 v99, v97
	s_add_i32 s8, s8, 0
	s_add_i32 s8, s8, 0x22000
	v_and_b32_e32 v56, 15, v106
	v_bfe_u32 v191, v106, 3, 3
	s_waitcnt vmcnt(10)
	v_and_b32_e32 v30, 0x7fffffff, v30
	s_waitcnt vmcnt(9)
	v_lshlrev_b32_e32 v32, 16, v0
	v_and_b32_e32 v33, 0xffff0000, v0
	v_lshlrev_b32_e32 v0, 16, v1
	v_and_b32_e32 v1, 0xffff0000, v1
	v_lshlrev_b32_e32 v34, 16, v2
	v_and_b32_e32 v35, 0xffff0000, v2
	v_lshlrev_b32_e32 v2, 16, v3
	v_and_b32_e32 v3, 0xffff0000, v3
	s_waitcnt vmcnt(8)
	v_lshlrev_b32_e32 v36, 16, v4
	v_and_b32_e32 v37, 0xffff0000, v4
	v_lshlrev_b32_e32 v4, 16, v5
	v_and_b32_e32 v5, 0xffff0000, v5
	v_lshlrev_b32_e32 v38, 16, v6
	v_and_b32_e32 v39, 0xffff0000, v6
	v_lshlrev_b32_e32 v6, 16, v7
	v_and_b32_e32 v7, 0xffff0000, v7
	s_waitcnt vmcnt(7)
	v_and_b32_e32 v40, 0x7fffffff, v31
	s_waitcnt vmcnt(6)
	v_lshlrev_b32_e32 v46, 16, v11
	v_pk_mul_f32 v[32:33], v[30:31], v[32:33] op_sel_hi:[0,1]
	v_pk_mul_f32 v[48:49], v[30:31], v[0:1] op_sel_hi:[0,1]
	v_pk_mul_f32 v[34:35], v[30:31], v[34:35] op_sel_hi:[0,1]
	v_pk_mul_f32 v[50:51], v[30:31], v[2:3] op_sel_hi:[0,1]
	v_pk_mul_f32 v[36:37], v[30:31], v[36:37] op_sel_hi:[0,1]
	v_pk_mul_f32 v[52:53], v[30:31], v[4:5] op_sel_hi:[0,1]
	v_pk_mul_f32 v[38:39], v[30:31], v[38:39] op_sel_hi:[0,1]
	v_pk_mul_f32 v[30:31], v[30:31], v[6:7] op_sel_hi:[0,1]
	v_and_b32_e32 v47, 0xffff0000, v11
	v_cvt_pk_bf16_f32 v0, v32, v33
	v_cvt_pk_bf16_f32 v7, v30, v31
	v_pk_mul_f32 v[32:33], v[40:41], v[46:47] op_sel_hi:[0,1]
	global_load_dwordx4 v[28:31], v[28:29], off offset:64
	v_lshlrev_b32_e32 v44, 16, v10
	v_and_b32_e32 v45, 0xffff0000, v10
	v_cvt_pk_bf16_f32 v11, v32, v33
	s_waitcnt vmcnt(6)
	v_lshlrev_b32_e32 v32, 16, v12
	v_and_b32_e32 v33, 0xffff0000, v12
	v_pk_mul_f32 v[44:45], v[40:41], v[44:45] op_sel_hi:[0,1]
	v_pk_mul_f32 v[32:33], v[40:41], v[32:33] op_sel_hi:[0,1]
	v_cvt_pk_bf16_f32 v10, v44, v45
	v_cvt_pk_bf16_f32 v12, v32, v33
	v_lshlrev_b32_e32 v32, 16, v13
	v_and_b32_e32 v33, 0xffff0000, v13
	v_add_u32_e32 v44, s18, v58
	v_pk_mul_f32 v[32:33], v[40:41], v[32:33] op_sel_hi:[0,1]
	v_ashrrev_i32_e32 v45, 31, v44
	v_lshlrev_b32_e32 v42, 16, v8
	v_and_b32_e32 v43, 0xffff0000, v8
	v_cvt_pk_bf16_f32 v13, v32, v33
	v_lshlrev_b64 v[32:33], 5, v[44:45]
	v_lshlrev_b32_e32 v8, 16, v9
	v_and_b32_e32 v9, 0xffff0000, v9
	v_pk_mul_f32 v[42:43], v[40:41], v[42:43] op_sel_hi:[0,1]
	v_cvt_pk_bf16_f32 v4, v36, v37
	v_lshl_add_u64 v[36:37], s[16:17], 0, v[32:33]
	v_pk_mul_f32 v[54:55], v[40:41], v[8:9] op_sel_hi:[0,1]
	v_cvt_pk_bf16_f32 v2, v34, v35
	v_cvt_pk_bf16_f32 v6, v38, v39
	v_cvt_pk_bf16_f32 v8, v42, v43
	v_lshlrev_b32_e32 v42, 16, v14
	global_load_dwordx4 v[32:35], v[36:37], off offset:16
	s_nop 0
	global_load_dwordx4 v[36:39], v[36:37], off
	v_and_b32_e32 v43, 0xffff0000, v14
	v_pk_mul_f32 v[42:43], v[40:41], v[42:43] op_sel_hi:[0,1]
	v_cvt_pk_bf16_f32 v14, v42, v43
	v_lshlrev_b32_e32 v42, 16, v15
	v_and_b32_e32 v43, 0xffff0000, v15
	v_pk_mul_f32 v[40:41], v[40:41], v[42:43] op_sel_hi:[0,1]
	v_cvt_pk_bf16_f32 v1, v48, v49
	v_cvt_pk_bf16_f32 v15, v40, v41
	s_waitcnt vmcnt(7)
	v_and_b32_e32 v48, 0x7fffffff, v57
	s_waitcnt vmcnt(6)
	v_lshlrev_b32_e32 v40, 16, v16
	v_and_b32_e32 v41, 0xffff0000, v16
	v_pk_mul_f32 v[40:41], v[48:49], v[40:41] op_sel_hi:[0,1]
	v_cvt_pk_bf16_f32 v16, v40, v41
	v_lshlrev_b32_e32 v40, 16, v17
	v_and_b32_e32 v41, 0xffff0000, v17
	v_pk_mul_f32 v[40:41], v[48:49], v[40:41] op_sel_hi:[0,1]
	v_cvt_pk_bf16_f32 v17, v40, v41
	v_lshlrev_b32_e32 v40, 16, v18
	v_and_b32_e32 v41, 0xffff0000, v18
	v_pk_mul_f32 v[40:41], v[48:49], v[40:41] op_sel_hi:[0,1]
	v_cvt_pk_bf16_f32 v18, v40, v41
	v_lshlrev_b32_e32 v40, 16, v19
	v_and_b32_e32 v41, 0xffff0000, v19
	v_pk_mul_f32 v[40:41], v[48:49], v[40:41] op_sel_hi:[0,1]
	v_cvt_pk_bf16_f32 v19, v40, v41
	v_add_u32_e32 v40, 4, v44
	v_ashrrev_i32_e32 v41, 31, v40
	v_lshlrev_b64 v[40:41], 5, v[40:41]
	v_lshl_add_u64 v[44:45], s[16:17], 0, v[40:41]
	global_load_dwordx4 v[40:43], v[44:45], off offset:16
	s_nop 0
	global_load_dwordx4 v[44:47], v[44:45], off
	v_cvt_pk_bf16_f32 v3, v50, v51
	s_waitcnt vmcnt(7)
	v_lshlrev_b32_e32 v50, 16, v20
	v_and_b32_e32 v51, 0xffff0000, v20
	v_pk_mul_f32 v[50:51], v[48:49], v[50:51] op_sel_hi:[0,1]
	v_cvt_pk_bf16_f32 v20, v50, v51
	v_lshlrev_b32_e32 v50, 16, v21
	v_and_b32_e32 v51, 0xffff0000, v21
	v_pk_mul_f32 v[50:51], v[48:49], v[50:51] op_sel_hi:[0,1]
	v_cvt_pk_bf16_f32 v21, v50, v51
	v_lshlrev_b32_e32 v50, 16, v22
	v_and_b32_e32 v51, 0xffff0000, v22
	v_pk_mul_f32 v[50:51], v[48:49], v[50:51] op_sel_hi:[0,1]
	v_cvt_pk_bf16_f32 v22, v50, v51
	v_lshlrev_b32_e32 v50, 16, v23
	v_and_b32_e32 v51, 0xffff0000, v23
	v_pk_mul_f32 v[48:49], v[48:49], v[50:51] op_sel_hi:[0,1]
	v_cvt_pk_bf16_f32 v23, v48, v49
	s_waitcnt vmcnt(6)
	v_and_b32_e32 v48, 0x7fffffff, v59
	s_waitcnt vmcnt(5)
	v_lshlrev_b32_e32 v50, 16, v24
	v_and_b32_e32 v51, 0xffff0000, v24
	v_pk_mul_f32 v[50:51], v[48:49], v[50:51] op_sel_hi:[0,1]
	v_cvt_pk_bf16_f32 v24, v50, v51
	v_lshlrev_b32_e32 v50, 16, v25
	v_and_b32_e32 v51, 0xffff0000, v25
	v_pk_mul_f32 v[50:51], v[48:49], v[50:51] op_sel_hi:[0,1]
	v_cvt_pk_bf16_f32 v25, v50, v51
	v_lshlrev_b32_e32 v50, 16, v26
	v_and_b32_e32 v51, 0xffff0000, v26
	v_pk_mul_f32 v[50:51], v[48:49], v[50:51] op_sel_hi:[0,1]
	v_cvt_pk_bf16_f32 v26, v50, v51
	v_lshlrev_b32_e32 v50, 16, v27
	v_and_b32_e32 v51, 0xffff0000, v27
	v_pk_mul_f32 v[50:51], v[48:49], v[50:51] op_sel_hi:[0,1]
	v_cvt_pk_bf16_f32 v27, v50, v51
	s_waitcnt vmcnt(4)
	v_lshlrev_b32_e32 v50, 16, v28
	v_and_b32_e32 v51, 0xffff0000, v28
	v_pk_mul_f32 v[50:51], v[48:49], v[50:51] op_sel_hi:[0,1]
	v_cvt_pk_bf16_f32 v28, v50, v51
	v_lshlrev_b32_e32 v50, 16, v29
	v_and_b32_e32 v51, 0xffff0000, v29
	v_pk_mul_f32 v[50:51], v[48:49], v[50:51] op_sel_hi:[0,1]
	v_cvt_pk_bf16_f32 v29, v50, v51
	v_lshlrev_b32_e32 v50, 16, v30
	v_and_b32_e32 v51, 0xffff0000, v30
	v_pk_mul_f32 v[50:51], v[48:49], v[50:51] op_sel_hi:[0,1]
	v_cvt_pk_bf16_f32 v30, v50, v51
	v_lshlrev_b32_e32 v50, 16, v31
	v_and_b32_e32 v51, 0xffff0000, v31
	v_pk_mul_f32 v[48:49], v[48:49], v[50:51] op_sel_hi:[0,1]
	s_waitcnt vmcnt(2)
	v_cmp_gt_f32_e32 vcc, 0, v36
	v_cvt_pk_bf16_f32 v31, v48, v49
	v_cvt_pk_bf16_f32 v5, v52, v53
	v_cndmask_b32_e64 v48, 0, -1.0, vcc
	v_cmp_nlt_f32_e32 vcc, 0, v36
	v_cvt_pk_bf16_f32 v9, v54, v55
	s_nop 0
	v_cndmask_b32_e32 v162, 1.0, v48, vcc
	v_cmp_gt_f32_e32 vcc, 0, v37
	s_nop 1
	v_cndmask_b32_e64 v36, 0, -1.0, vcc
	v_cmp_nlt_f32_e32 vcc, 0, v37
	s_nop 1
	v_cndmask_b32_e32 v163, 1.0, v36, vcc
	v_cmp_gt_f32_e32 vcc, 0, v38
	s_nop 1
	v_cndmask_b32_e64 v36, 0, -1.0, vcc
	v_cmp_nlt_f32_e32 vcc, 0, v38
	s_nop 1
	v_cndmask_b32_e32 v164, 1.0, v36, vcc
	v_cmp_gt_f32_e32 vcc, 0, v39
	s_nop 1
	v_cndmask_b32_e64 v36, 0, -1.0, vcc
	v_cmp_nlt_f32_e32 vcc, 0, v39
	s_nop 1
	v_cndmask_b32_e32 v165, 1.0, v36, vcc
	v_cmp_gt_f32_e32 vcc, 0, v32
	s_nop 1
	v_cndmask_b32_e64 v36, 0, -1.0, vcc
	v_cmp_nlt_f32_e32 vcc, 0, v32
	s_nop 1
	v_cndmask_b32_e32 v166, 1.0, v36, vcc
	v_cmp_gt_f32_e32 vcc, 0, v33
	s_nop 1
	v_cndmask_b32_e64 v32, 0, -1.0, vcc
	v_cmp_nlt_f32_e32 vcc, 0, v33
	v_lshlrev_b32_e32 v33, 2, v56
	s_nop 0
	v_cndmask_b32_e32 v167, 1.0, v32, vcc
	v_cmp_gt_f32_e32 vcc, 0, v34
	s_nop 1
	v_cndmask_b32_e64 v32, 0, -1.0, vcc
	v_cmp_nlt_f32_e32 vcc, 0, v34
	s_nop 1
	v_cndmask_b32_e32 v168, 1.0, v32, vcc
	v_cmp_gt_f32_e32 vcc, 0, v35
	s_nop 1
	v_cndmask_b32_e64 v32, 0, -1.0, vcc
	v_cmp_nlt_f32_e32 vcc, 0, v35
	s_nop 1
	v_cndmask_b32_e32 v169, 1.0, v32, vcc
	s_waitcnt vmcnt(0)
	v_cmp_gt_f32_e32 vcc, 0, v44
	s_nop 1
	v_cndmask_b32_e64 v32, 0, -1.0, vcc
	v_cmp_nlt_f32_e32 vcc, 0, v44
	s_nop 1
	v_cndmask_b32_e32 v170, 1.0, v32, vcc
	v_cmp_gt_f32_e32 vcc, 0, v45
	s_nop 1
	v_cndmask_b32_e64 v32, 0, -1.0, vcc
	v_cmp_nlt_f32_e32 vcc, 0, v45
	s_nop 1
	v_cndmask_b32_e32 v171, 1.0, v32, vcc
	v_cmp_gt_f32_e32 vcc, 0, v46
	s_nop 1
	v_cndmask_b32_e64 v32, 0, -1.0, vcc
	v_cmp_nlt_f32_e32 vcc, 0, v46
	s_nop 1
	v_cndmask_b32_e32 v172, 1.0, v32, vcc
	v_cmp_gt_f32_e32 vcc, 0, v47
	s_nop 1
	v_cndmask_b32_e64 v32, 0, -1.0, vcc
	v_cmp_nlt_f32_e32 vcc, 0, v47
	s_nop 1
	v_cndmask_b32_e32 v173, 1.0, v32, vcc
	v_cmp_gt_f32_e32 vcc, 0, v40
	s_nop 1
	v_cndmask_b32_e64 v32, 0, -1.0, vcc
	v_cmp_nlt_f32_e32 vcc, 0, v40
	s_nop 1
	v_cndmask_b32_e32 v174, 1.0, v32, vcc
	v_cmp_gt_f32_e32 vcc, 0, v41
	s_nop 1
	v_cndmask_b32_e64 v32, 0, -1.0, vcc
	v_cmp_nlt_f32_e32 vcc, 0, v41
	s_nop 1
	v_cndmask_b32_e32 v175, 1.0, v32, vcc
	v_cmp_gt_f32_e32 vcc, 0, v42
	s_nop 1
	v_cndmask_b32_e64 v32, 0, -1.0, vcc
	v_cmp_nlt_f32_e32 vcc, 0, v42
	s_nop 1
	v_cndmask_b32_e32 v176, 1.0, v32, vcc
	v_cmp_gt_f32_e32 vcc, 0, v43
	s_nop 1
	v_cndmask_b32_e64 v32, 0, -1.0, vcc
	v_cmp_nlt_f32_e32 vcc, 0, v43
	s_nop 1
	v_cndmask_b32_e32 v177, 1.0, v32, vcc
	v_lshlrev_b32_e32 v32, 4, v106
	v_and_b32_e32 v98, 0x70, v32
	v_lshl_add_u64 v[100:101], s[6:7], 0, v[98:99]
	s_min_u32 s7, s19, 0x1000
	s_add_i32 s7, s7, 31
	v_mov_b32_e32 v32, s8
	s_lshl_b32 s6, s12, 7
	s_lshr_b32 s7, s7, 5
	v_mad_u32_u24 v178, v191, s26, v32
	v_mad_u32_u24 v179, v56, s26, v32
	v_lshlrev_b32_e32 v32, 14, v58
	s_add_i32 s6, s6, 0
	s_sub_i32 s8, s7, s12
	s_cmp_lt_i32 s8, 1
	v_add3_u32 v180, s6, v32, v33
	s_cbranch_scc1 .LBB0_826
	s_add_i32 s6, s8, 7
	s_lshr_b32 s7, s6, 29
	s_add_i32 s6, s6, s7
	s_ashr_i32 s6, s6, 3
	s_add_i32 s7, s6, -1
	s_lshl_b32 s9, s7, 3
	s_cmp_lt_u32 s8, 9
	s_cselect_b32 s40, s9, 8
	s_add_i32 s40, s40, s12
	s_cmp_lt_u32 s8, 17
	s_cselect_b32 s8, s9, 16
	s_add_i32 s8, s8, s12
	v_lshl_or_b32 v102, s12, 5, v191
	v_lshl_or_b32 v40, s40, 5, v191
	v_lshl_or_b32 v48, s8, 5, v191
	v_ashrrev_i32_e32 v103, 31, v102
	v_ashrrev_i32_e32 v41, 31, v40
	v_ashrrev_i32_e32 v49, 31, v48
	v_lshlrev_b64 v[32:33], 7, v[102:103]
	v_lshlrev_b64 v[40:41], 7, v[40:41]
	v_lshlrev_b64 v[48:49], 7, v[48:49]
	v_lshl_add_u64 v[36:37], v[100:101], 0, v[32:33]
	v_lshl_add_u64 v[44:45], v[100:101], 0, v[40:41]
	v_lshl_add_u64 v[52:53], v[100:101], 0, v[48:49]
	global_load_dwordx4 v[64:67], v[36:37], off
	global_load_dwordx4 v[68:71], v[36:37], off offset:1024
	global_load_dwordx4 v[32:35], v[36:37], off offset:2048
	s_nop 0
	global_load_dwordx4 v[36:39], v[36:37], off offset:3072
	s_nop 0
	global_load_dwordx4 v[72:75], v[44:45], off
	global_load_dwordx4 v[76:79], v[44:45], off offset:1024
	global_load_dwordx4 v[40:43], v[44:45], off offset:2048
	s_nop 0
	global_load_dwordx4 v[44:47], v[44:45], off offset:3072
	s_nop 0
	global_load_dwordx4 v[80:83], v[52:53], off
	global_load_dwordx4 v[84:87], v[52:53], off offset:1024
	global_load_dwordx4 v[48:51], v[52:53], off offset:2048
	s_nop 0
	global_load_dwordx4 v[52:55], v[52:53], off offset:3072
	s_and_saveexec_b64 s[98:99], s[28:29]
	s_cbranch_execz .Lselq_skip
	v_mov_b32_e32 v240, 1
	global_atomic_add v240, v97, v240, s[10:11] sc0
.Lselq_skip:
	s_or_b64 exec, exec, s[98:99]
	s_mov_b32 s8, 6
	v_mov_b32_e32 v99, v180
	s_branch .LBB0_820

.LBB0_1141:
	s_waitcnt lgkmcnt(0)
	s_add_i32 s6, s18, s12
	v_lshl_add_u32 v0, v96, 2, s40
	s_ashr_i32 s7, s6, 31
	ds_read_b128 v[0:3], v0
	s_lshl_b64 s[6:7], s[6:7], 10
	s_add_u32 s6, s24, s6
	s_addc_u32 s7, s25, s7
	v_lshl_add_u64 v[4:5], v[96:97], 2, s[6:7]
	s_waitcnt lgkmcnt(0)
	global_store_dwordx4 v[4:5], v[0:3], off
	s_barrier
	s_and_saveexec_b64 s[6:7], s[28:29]
	s_cbranch_execz .LBB0_808
	v_mov_b32_e32 v0, s3
	s_waitcnt vmcnt(1)
	ds_write_b32 v0, v240
	s_branch .LBB0_808

	.amdhsa_kernel _Z14fwd_megakernel4Args
		.amdhsa_group_segment_fixed_size 0
		.amdhsa_private_segment_fixed_size 0
		.amdhsa_kernarg_size 480
		.amdhsa_user_sgpr_count 2
		.amdhsa_user_sgpr_dispatch_ptr 0
		.amdhsa_user_sgpr_queue_ptr 0
		.amdhsa_user_sgpr_kernarg_segment_ptr 1
		.amdhsa_user_sgpr_dispatch_id 0
		.amdhsa_user_sgpr_kernarg_preload_length 0
		.amdhsa_user_sgpr_kernarg_preload_offset 0
		.amdhsa_user_sgpr_private_segment_size 0
		.amdhsa_uses_dynamic_stack 0
		.amdhsa_enable_private_segment 0
		.amdhsa_system_sgpr_workgroup_id_x 1
		.amdhsa_system_sgpr_workgroup_id_y 0
		.amdhsa_system_sgpr_workgroup_id_z 0
		.amdhsa_system_sgpr_workgroup_info 0
		.amdhsa_system_vgpr_workitem_id 2
		.amdhsa_next_free_vgpr 249
		.amdhsa_next_free_sgpr 102
		.amdhsa_accum_offset 252
		.amdhsa_reserve_vcc 1
		.amdhsa_float_round_mode_32 0
		.amdhsa_float_round_mode_16_64 0
		.amdhsa_float_denorm_mode_32 3
		.amdhsa_float_denorm_mode_16_64 3
		.amdhsa_dx10_clamp 1
		.amdhsa_ieee_mode 1
		.amdhsa_fp16_overflow 0
		.amdhsa_tg_split 0
		.amdhsa_exception_fp_ieee_invalid_op 0
		.amdhsa_exception_fp_denorm_src 0
		.amdhsa_exception_fp_ieee_div_zero 0
		.amdhsa_exception_fp_ieee_overflow 0
		.amdhsa_exception_fp_ieee_underflow 0
		.amdhsa_exception_fp_ieee_inexact 0
		.amdhsa_exception_int_div_zero 0
	.end_amdhsa_kernel

amdhsa.kernels:
  - .agpr_count:     0
    .args:
      - .offset:         0
        .size:           224
        .value_kind:     by_value
      - .offset:         224
        .size:           4
        .value_kind:     hidden_block_count_x
      - .offset:         228
        .size:           4
        .value_kind:     hidden_block_count_y
      - .offset:         232
        .size:           4
        .value_kind:     hidden_block_count_z
      - .offset:         236
        .size:           2
        .value_kind:     hidden_group_size_x
      - .offset:         238
        .size:           2
        .value_kind:     hidden_group_size_y
      - .offset:         240
        .size:           2
        .value_kind:     hidden_group_size_z
      - .offset:         242
        .size:           2
        .value_kind:     hidden_remainder_x
      - .offset:         244
        .size:           2
        .value_kind:     hidden_remainder_y
      - .offset:         246
        .size:           2
        .value_kind:     hidden_remainder_z
      - .offset:         264
        .size:           8
        .value_kind:     hidden_global_offset_x
      - .offset:         272
        .size:           8
        .value_kind:     hidden_global_offset_y
      - .offset:         280
        .size:           8
        .value_kind:     hidden_global_offset_z
      - .offset:         288
        .size:           2
        .value_kind:     hidden_grid_dims
      - .offset:         312
        .size:           8
        .value_kind:     hidden_multigrid_sync_arg
      - .offset:         344
        .size:           4
        .value_kind:     hidden_dynamic_lds_size
    .group_segment_fixed_size: 0
    .kernarg_segment_align: 8
    .kernarg_segment_size: 480
    .language:       OpenCL C
    .language_version:
      - 2
      - 0
    .max_flat_workgroup_size: 512
    .name:           _Z14fwd_megakernel4Args
    .private_segment_fixed_size: 0
    .sgpr_count:     108
    .sgpr_spill_count: 4
    .symbol:         _Z14fwd_megakernel4Args.kd
    .uniform_work_group_size: 1
    .uses_dynamic_stack: false
    .vgpr_count:     249
    .vgpr_spill_count: 0
    .wavefront_size: 64
